# P1 GEMM unit order with 8 row panels x 4 column tiles per XCD round (group size 8) instead of 4x8, otherwise v93
# baseline (speedup 1.0000x reference)
; #define PG8_STAGE(bufoff, gbase, voff) do { _Pragma("unroll") for (int _i = 0; _i < 2; ++_i) \
;         __builtin_amdgcn_global_load_lds((const unsigned*)((const char*)(gbase) + (voff)[_i]), (LAS unsigned*)(lds + (bufoff) + ldsw + _i * 8192), 16, 0, 0); } while (0)
; #define PG8_WAIT_V(n) asm volatile("s_waitcnt vmcnt(" #n ")" ::: "memory")
; #define PG8_BAR __builtin_amdgcn_s_barrier()
;     __host__ __device__ bool next(int i, Unit& u) const {
;     ...
;         int wgid = (int)L; { const int q = nwg / NXCD, r = nwg % NXCD, xcd = wgid % NXCD, off = wgid / NXCD; wgid = (xcd < r ? xcd * (q + 1) : r * (q + 1) + (xcd - r) * q) + off; }
;         const int nig = WGM * nN, gid = wgid / nig, fm = gid * WGM, gsz = (nM - fm) < WGM ? (nM - fm) : WGM;
;         u.pm = fm + ((wgid % nig) % gsz); u.pn = (wgid % nig) / gsz; return true;
; template <class Epi, class Sched>
; __device__ __forceinline__ void gemm_phase(LAS unsigned char* lds, const Gemm g, const Sched& S, const Epi& E) {
;     ...
;     const char* cA = (const char*)g.A + (size_t)cur.pm * tstepA; const char* cB = (const char*)g.Bt + (size_t)cur.pn * tstepB;
;     PG8_STAGE(PG8_SB(0, 0), cB, voffB); PG8_STAGE(PG8_SB(0, 1), cB + hstepB, voffB); PG8_STAGE(PG8_SA(0, 0), cA, voffA); PG8_STAGE(PG8_SA(0, 1), cA + hstepA, voffA);
;     if (wr == 1) PG8_BAR;
;     PG8_WAIT_V(2); PG8_BAR;
;     PG8_STAGE(PG8_SB(1, 0), cB + kstep, voffB); PG8_STAGE(PG8_SA(1, 0), cA + kstep, voffA); PG8_STAGE(PG8_SB(1, 1), cB + hstepB + kstep, voffB);
;     PG8_WAIT_V(6); PG8_BAR;
.LBB0_164:
	v_and_b32_e32 v0, 32, v188
	v_lshrrev_b32_e32 v1, 1, v188
	s_ashr_i32 s4, s7, 3
	v_bfe_u32 v8, v188, 2, 4
	v_bitop3_b32 v9, v45, v0, 48 bitop3:0x6c
	v_and_b32_e32 v10, 64, v188
	v_and_b32_e32 v1, 24, v1
	v_and_b32_e32 v2, 4, v47
	v_bfe_u32 v3, v188, 2, 2
	v_or_b32_e32 v0, v9, v10
	v_or3_b32 v1, v2, v3, v1
	v_or_b32_e32 v2, v42, v8
	s_movk_i32 s7, 0x60
	v_add_u32_e32 v11, 0x2000, v45
	s_add_i32 s4, s6, s4
	v_and_or_b32 v3, v46, s7, v1
	v_lshl_or_b32 v128, v2, 12, v0
	v_lshrrev_b32_e32 v2, 7, v11
	s_movk_i32 s7, 0xf0
	s_mul_hi_i32 s6, s4, 0xb21642c9
	v_lshl_or_b32 v130, v3, 12, v0
	v_and_or_b32 v3, v2, s7, v8
	s_movk_i32 s7, 0xe0
	s_add_i32 s6, s6, s4
	v_and_or_b32 v1, v2, s7, v1
	s_lshr_b32 s7, s6, 31
	s_ashr_i32 s6, s6, 8
	s_add_i32 s6, s6, s7
	s_lshl_b32 s13, s6, 3
	s_sub_i32 s7, 0x42, s13
	s_mulk_i32 s6, 0x170
	s_min_u32 s15, s7, 8
	s_sub_i32 s16, s4, s6
	v_lshl_or_b32 v134, v1, 12, v0
	s_mov_b32 s4, s16
	v_cvt_f32_ubyte0_e32 v1, s15
	v_lshl_or_b32 v132, v3, 12, v0
	v_cvt_f32_i32_e32 v0, s4
	v_rcp_iflag_f32_e32 v2, v1
	s_lshr_b32 s12, s14, 6
	s_ashr_i32 s4, s4, 30
	s_lshr_b32 s5, s14, 8
	v_mul_f32_e32 v2, v0, v2
	v_trunc_f32_e32 v2, v2
	v_fma_f32 v0, -v2, v1, v0
	v_cvt_i32_f32_e32 v2, v2
	s_lshl_b32 s36, s12, 10
	s_or_b32 s4, s4, 1
	v_cmp_ge_f32_e64 s[6:7], |v0|, v1
	s_and_b64 s[6:7], s[6:7], exec
	s_cselect_b32 s4, s4, 0
	v_readfirstlane_b32 s6, v2
	s_add_i32 s4, s6, s4
	s_mul_i32 s6, s4, s15
	s_sub_i32 s6, s16, s6
	s_sext_i32_i8 s6, s6
	s_add_i32 s24, s13, s6
	s_ashr_i32 s25, s24, 31
	s_bfe_i64 s[16:17], s[4:5], 0x80000
	s_lshl_b64 s[6:7], s[24:25], 20
	s_lshl_b64 s[16:17], s[16:17], 20
	s_add_u32 s28, s8, s16
	s_addc_u32 s29, s9, s17
	s_add_i32 s25, s36, 0
	s_add_i32 m0, s25, 0x10000
	v_mov_b32_e32 v131, 0
	global_load_lds_dwordx4 v130, s[28:29]
	s_add_i32 m0, s25, 0x12000
	s_add_u32 s16, s28, 0x80000
	global_load_lds_dwordx4 v134, s[28:29]
	s_addc_u32 s17, s29, 0
	s_add_i32 m0, s25, 0x14000
	v_mov_b32_e32 v135, v131
	global_load_lds_dwordx4 v130, s[16:17]
	s_add_i32 m0, s25, 0x16000
	s_add_u32 s26, s10, s6
	s_addc_u32 s27, s11, s7
	s_add_i32 s37, s25, 0x2000
	global_load_lds_dwordx4 v134, s[16:17]
	s_mov_b32 m0, s25
	s_add_u32 s6, s26, 0x80000
	global_load_lds_dwordx4 v128, s[26:27]
	s_mov_b32 m0, s37
	s_addc_u32 s7, s27, 0
	s_add_i32 s38, s25, 0x4000
	global_load_lds_dwordx4 v132, s[26:27]
	s_mov_b32 m0, s38
	s_add_i32 s39, s25, 0x6000
	global_load_lds_dwordx4 v128, s[6:7]
	s_mov_b32 m0, s39
	v_mov_b32_e32 v129, v131
	global_load_lds_dwordx4 v132, s[6:7]
	v_mov_b32_e32 v133, v131
	s_cmp_eq_u32 s5, 1
	s_mov_b32 s40, 0
	v_lshl_add_u64 v[6:7], s[28:29], 0, v[130:131]
	v_lshl_add_u64 v[4:5], s[28:29], 0, v[134:135]
	v_lshl_add_u64 v[0:1], s[26:27], 0, v[128:129]
	s_cselect_b64 s[6:7], -1, 0
	s_cmp_lg_u32 s5, 1
	v_lshl_add_u64 v[2:3], s[26:27], 0, v[132:133]
	s_cbranch_scc1 .LBB0_166
	s_barrier

;     __host__ __device__ bool next(int i, Unit& u) const {
;     ...
;         int wgid = (int)L; { const int q = nwg / NXCD, r = nwg % NXCD, xcd = wgid % NXCD, off = wgid / NXCD; wgid = (xcd < r ? xcd * (q + 1) : r * (q + 1) + (xcd - r) * q) + off; }
;         const int nig = WGM * nN, gid = wgid / nig, fm = gid * WGM, gsz = (nM - fm) < WGM ? (nM - fm) : WGM;
;         u.pm = fm + ((wgid % nig) % gsz); u.pn = (wgid % nig) / gsz; return true;
.LBB0_174:
	s_ashr_i32 s16, s18, 3
	s_add_i32 s16, s20, s16
	s_mul_hi_i32 s17, s16, 0xb21642c9
	s_add_i32 s17, s17, s16
	s_lshr_b32 s18, s17, 31
	s_ashr_i32 s17, s17, 8
	s_add_i32 s17, s17, s18
	s_lshl_b32 s18, s17, 3
	s_sub_i32 s19, 0x42, s18
	s_min_i32 s19, s19, 8
	s_abs_i32 s20, s19
	v_cvt_f32_u32_e32 v0, s20
	s_sub_i32 s22, 0, s20
	s_mulk_i32 s17, 0x170
	s_sub_i32 s17, s16, s17
	v_rcp_iflag_f32_e32 v0, v0
	s_abs_i32 s16, s17
	s_xor_b32 s21, s17, s19
	s_ashr_i32 s21, s21, 31
	v_mul_f32_e32 v0, 0x4f7ffffe, v0
	v_cvt_u32_f32_e32 v0, v0
	s_nop 0
	v_readfirstlane_b32 s23, v0
	s_mul_i32 s22, s22, s23
	s_mul_hi_u32 s22, s23, s22
	s_add_i32 s23, s23, s22
	s_mul_hi_u32 s22, s16, s23
	s_mul_i32 s23, s22, s20
	s_sub_i32 s16, s16, s23
	s_add_i32 s30, s22, 1
	s_sub_i32 s23, s16, s20
	s_cmp_ge_u32 s16, s20
	s_cselect_b32 s22, s30, s22
	s_cselect_b32 s16, s23, s16
	s_add_i32 s23, s22, 1
	s_cmp_ge_u32 s16, s20
	s_cselect_b32 s16, s23, s22
	s_xor_b32 s16, s16, s21
	s_sub_i32 s16, s16, s21
	s_mul_i32 s19, s16, s19
	s_sub_i32 s17, s17, s19
	s_add_i32 s18, s18, s17
